# combo2 + last 64-bit VALU address op removed from the P5/P7/P8 K-loops (SGPR copy instead)
# speedup vs baseline: 1.0022x; 1.0022x over previous
.LBB0_877:
	s_add_u32 s62, s60, 0x100
	s_addc_u32 s63, s61, 0
	s_add_i32 s34, 0, 0x10000
	s_cmp_eq_u32 s49, 60
	s_cselect_b32 s67, s51, s63
	s_cselect_b32 s66, s50, s62
	s_cselect_b32 s65, s53, s28
	s_cselect_b32 s64, s52, s13
	s_add_i32 s55, 0, 0x14000
	ds_read_b128 v[132:135], v190 offset:0
	ds_read_b128 v[136:139], v190 offset:1024
	ds_read_b128 v[140:143], v190 offset:2048
	ds_read_b128 v[144:147], v190 offset:3072
	ds_read_b128 v[148:151], v190 offset:16384
	ds_read_b128 v[152:155], v190 offset:17408
	ds_read_b128 v[168:171], v190 offset:18432
	ds_read_b128 v[172:175], v190 offset:19456
	s_add_i32 m0, s29, 0xc000
	ds_read_b128 v[176:179], v189
	ds_read_b128 v[180:183], v189 offset:1024
	ds_read_b128 v[184:187], v189 offset:2048
	ds_read_b128 v[192:195], v189 offset:3072
	ds_read_b128 v[210:213], v189 offset:4096
	ds_read_b128 v[234:237], v189 offset:5120
	ds_read_b128 v[238:241], v189 offset:6144
	ds_read_b128 v[242:245], v189 offset:7168
	global_load_lds_dwordx4 v164, s[60:61]
	s_add_i32 m0, s29, 0xe000
	s_nop 0
	global_load_lds_dwordx4 v166, s[60:61]
	s_waitcnt vmcnt(8) lgkmcnt(0)
	s_barrier
	v_mfma_f32_16x16x32_bf16 v[128:131], v[132:135], v[176:179], v[128:131]
	v_mfma_f32_16x16x32_bf16 v[124:127], v[140:143], v[176:179], v[124:127]
	v_mfma_f32_16x16x32_bf16 v[112:115], v[132:135], v[184:187], v[112:115]
	v_mfma_f32_16x16x32_bf16 v[108:111], v[140:143], v[184:187], v[108:111]
	v_mfma_f32_16x16x32_bf16 v[96:99], v[132:135], v[210:213], v[96:99]
	v_mfma_f32_16x16x32_bf16 v[92:95], v[140:143], v[210:213], v[92:95]
	v_mfma_f32_16x16x32_bf16 v[80:83], v[132:135], v[238:241], v[80:83]
	v_mfma_f32_16x16x32_bf16 v[76:79], v[140:143], v[238:241], v[76:79]
	v_mfma_f32_16x16x32_bf16 v[128:131], v[136:139], v[180:183], v[128:131]
	v_mfma_f32_16x16x32_bf16 v[124:127], v[144:147], v[180:183], v[124:127]
	v_mfma_f32_16x16x32_bf16 v[112:115], v[136:139], v[192:195], v[112:115]
	v_mfma_f32_16x16x32_bf16 v[108:111], v[144:147], v[192:195], v[108:111]
	v_mfma_f32_16x16x32_bf16 v[96:99], v[136:139], v[234:237], v[96:99]
	v_mfma_f32_16x16x32_bf16 v[92:95], v[144:147], v[234:237], v[92:95]
	v_mfma_f32_16x16x32_bf16 v[80:83], v[136:139], v[242:245], v[80:83]
	v_mfma_f32_16x16x32_bf16 v[76:79], v[144:147], v[242:245], v[76:79]
	v_mfma_f32_16x16x32_bf16 v[120:123], v[148:151], v[176:179], v[120:123]
	v_mfma_f32_16x16x32_bf16 v[116:119], v[168:171], v[176:179], v[116:119]
	v_mfma_f32_16x16x32_bf16 v[104:107], v[148:151], v[184:187], v[104:107]
	v_mfma_f32_16x16x32_bf16 v[100:103], v[168:171], v[184:187], v[100:103]
	v_mfma_f32_16x16x32_bf16 v[88:91], v[148:151], v[210:213], v[88:91]
	v_mfma_f32_16x16x32_bf16 v[84:87], v[168:171], v[210:213], v[84:87]
	v_mfma_f32_16x16x32_bf16 v[72:75], v[148:151], v[238:241], v[72:75]
	v_mfma_f32_16x16x32_bf16 v[68:71], v[168:171], v[238:241], v[68:71]
	v_mfma_f32_16x16x32_bf16 v[120:123], v[152:155], v[180:183], v[120:123]
	v_mfma_f32_16x16x32_bf16 v[116:119], v[172:175], v[180:183], v[116:119]
	v_mfma_f32_16x16x32_bf16 v[104:107], v[152:155], v[192:195], v[104:107]
	v_mfma_f32_16x16x32_bf16 v[100:103], v[172:175], v[192:195], v[100:103]
	v_mfma_f32_16x16x32_bf16 v[88:91], v[152:155], v[234:237], v[88:91]
	v_mfma_f32_16x16x32_bf16 v[84:87], v[172:175], v[234:237], v[84:87]
	v_mfma_f32_16x16x32_bf16 v[72:75], v[152:155], v[242:245], v[72:75]
	v_mfma_f32_16x16x32_bf16 v[68:71], v[172:175], v[242:245], v[68:71]
	s_barrier
	s_add_i32 s34, s34, s0
	s_mov_b32 m0, s34
	ds_read_b128 v[176:179], v189 offset:16384
	ds_read_b128 v[180:183], v189 offset:17408
	ds_read_b128 v[184:187], v189 offset:18432
	ds_read_b128 v[192:195], v189 offset:19456
	ds_read_b128 v[210:213], v189 offset:20480
	ds_read_b128 v[234:237], v189 offset:21504
	ds_read_b128 v[238:241], v189 offset:22528
	ds_read_b128 v[242:245], v189 offset:23552
	global_load_lds_dwordx4 v156, s[64:65]
	s_add_i32 m0, s34, 0x2000
	s_add_u32 s34, s64, 0x4000
	s_addc_u32 s35, s65, 0
	s_add_i32 s55, s55, s0
	global_load_lds_dwordx4 v160, s[64:65]
	s_mov_b32 m0, s55
	s_nop 0
	global_load_lds_dwordx4 v156, s[34:35]
	s_add_i32 m0, s55, 0x2000
	s_nop 0
	global_load_lds_dwordx4 v160, s[34:35]
	s_mov_b32 m0, s29
	s_nop 0
	global_load_lds_dwordx4 v158, s[66:67]
	s_mov_b32 m0, s45
	s_nop 0
	global_load_lds_dwordx4 v162, s[66:67]
	s_waitcnt vmcnt(8) lgkmcnt(0)
	s_barrier
	v_mfma_f32_16x16x32_bf16 v[64:67], v[132:135], v[176:179], v[64:67]
	v_mfma_f32_16x16x32_bf16 v[60:63], v[140:143], v[176:179], v[60:63]
	v_mfma_f32_16x16x32_bf16 v[48:51], v[132:135], v[184:187], v[48:51]
	v_mfma_f32_16x16x32_bf16 v[44:47], v[140:143], v[184:187], v[44:47]
	v_mfma_f32_16x16x32_bf16 v[30:33], v[132:135], v[210:213], v[30:33]
	v_mfma_f32_16x16x32_bf16 v[26:29], v[140:143], v[210:213], v[26:29]
	v_mfma_f32_16x16x32_bf16 v[14:17], v[132:135], v[238:241], v[14:17]
	v_mfma_f32_16x16x32_bf16 v[10:13], v[140:143], v[238:241], v[10:13]
	v_mfma_f32_16x16x32_bf16 v[64:67], v[136:139], v[180:183], v[64:67]
	v_mfma_f32_16x16x32_bf16 v[60:63], v[144:147], v[180:183], v[60:63]
	v_mfma_f32_16x16x32_bf16 v[48:51], v[136:139], v[192:195], v[48:51]
	v_mfma_f32_16x16x32_bf16 v[44:47], v[144:147], v[192:195], v[44:47]
	v_mfma_f32_16x16x32_bf16 v[30:33], v[136:139], v[234:237], v[30:33]
	v_mfma_f32_16x16x32_bf16 v[26:29], v[144:147], v[234:237], v[26:29]
	v_mfma_f32_16x16x32_bf16 v[14:17], v[136:139], v[242:245], v[14:17]
	v_mfma_f32_16x16x32_bf16 v[10:13], v[144:147], v[242:245], v[10:13]
	v_mfma_f32_16x16x32_bf16 v[56:59], v[148:151], v[176:179], v[56:59]
	v_mfma_f32_16x16x32_bf16 v[52:55], v[168:171], v[176:179], v[52:55]
	v_mfma_f32_16x16x32_bf16 v[40:43], v[148:151], v[184:187], v[40:43]
	v_mfma_f32_16x16x32_bf16 v[36:39], v[168:171], v[184:187], v[36:39]
	v_mfma_f32_16x16x32_bf16 v[22:25], v[148:151], v[210:213], v[22:25]
	v_mfma_f32_16x16x32_bf16 v[18:21], v[168:171], v[210:213], v[18:21]
	v_mfma_f32_16x16x32_bf16 v[6:9], v[148:151], v[238:241], v[6:9]
	v_mfma_f32_16x16x32_bf16 v[2:5], v[168:171], v[238:241], v[2:5]
	v_mfma_f32_16x16x32_bf16 v[56:59], v[152:155], v[180:183], v[56:59]
	v_mfma_f32_16x16x32_bf16 v[52:55], v[172:175], v[180:183], v[52:55]
	v_mfma_f32_16x16x32_bf16 v[40:43], v[152:155], v[192:195], v[40:43]
	v_mfma_f32_16x16x32_bf16 v[36:39], v[172:175], v[192:195], v[36:39]
	v_mfma_f32_16x16x32_bf16 v[22:25], v[152:155], v[234:237], v[22:25]
	v_mfma_f32_16x16x32_bf16 v[18:21], v[172:175], v[234:237], v[18:21]
	v_mfma_f32_16x16x32_bf16 v[6:9], v[152:155], v[242:245], v[6:9]
	v_mfma_f32_16x16x32_bf16 v[2:5], v[172:175], v[242:245], v[2:5]
	s_barrier
	s_add_i32 s55, 0, 0x18000
	s_add_i32 s58, 0, 0x1c000
	ds_read_b128 v[132:135], v190 offset:32768
	ds_read_b128 v[136:139], v190 offset:33792
	ds_read_b128 v[140:143], v190 offset:34816
	ds_read_b128 v[144:147], v190 offset:35840
	ds_read_b128 v[148:151], v190 offset:49152
	ds_read_b128 v[152:155], v190 offset:50176
	ds_read_b128 v[168:171], v190 offset:51200
	ds_read_b128 v[172:175], v190 offset:52224
	s_add_u32 s34, s66, 0x100000
	s_addc_u32 s35, s67, 0
	s_mov_b32 m0, s82
	ds_read_b128 v[176:179], v189 offset:32768
	ds_read_b128 v[180:183], v189 offset:33792
	ds_read_b128 v[184:187], v189 offset:34816
	ds_read_b128 v[192:195], v189 offset:35840
	ds_read_b128 v[210:213], v189 offset:36864
	ds_read_b128 v[234:237], v189 offset:37888
	ds_read_b128 v[238:241], v189 offset:38912
	ds_read_b128 v[242:245], v189 offset:39936
	global_load_lds_dwordx4 v158, s[34:35]
	s_mov_b32 m0, s90
	s_nop 0
	global_load_lds_dwordx4 v162, s[34:35]
	s_waitcnt vmcnt(8) lgkmcnt(0)
	s_barrier
	v_mfma_f32_16x16x32_bf16 v[128:131], v[132:135], v[176:179], v[128:131]
	v_mfma_f32_16x16x32_bf16 v[124:127], v[140:143], v[176:179], v[124:127]
	v_mfma_f32_16x16x32_bf16 v[112:115], v[132:135], v[184:187], v[112:115]
	v_mfma_f32_16x16x32_bf16 v[108:111], v[140:143], v[184:187], v[108:111]
	v_mfma_f32_16x16x32_bf16 v[96:99], v[132:135], v[210:213], v[96:99]
	v_mfma_f32_16x16x32_bf16 v[92:95], v[140:143], v[210:213], v[92:95]
	v_mfma_f32_16x16x32_bf16 v[80:83], v[132:135], v[238:241], v[80:83]
	v_mfma_f32_16x16x32_bf16 v[76:79], v[140:143], v[238:241], v[76:79]
	v_mfma_f32_16x16x32_bf16 v[128:131], v[136:139], v[180:183], v[128:131]
	v_mfma_f32_16x16x32_bf16 v[124:127], v[144:147], v[180:183], v[124:127]
	v_mfma_f32_16x16x32_bf16 v[112:115], v[136:139], v[192:195], v[112:115]
	v_mfma_f32_16x16x32_bf16 v[108:111], v[144:147], v[192:195], v[108:111]
	v_mfma_f32_16x16x32_bf16 v[96:99], v[136:139], v[234:237], v[96:99]
	v_mfma_f32_16x16x32_bf16 v[92:95], v[144:147], v[234:237], v[92:95]
	v_mfma_f32_16x16x32_bf16 v[80:83], v[136:139], v[242:245], v[80:83]
	v_mfma_f32_16x16x32_bf16 v[76:79], v[144:147], v[242:245], v[76:79]
	v_mfma_f32_16x16x32_bf16 v[120:123], v[148:151], v[176:179], v[120:123]
	v_mfma_f32_16x16x32_bf16 v[116:119], v[168:171], v[176:179], v[116:119]
	v_mfma_f32_16x16x32_bf16 v[104:107], v[148:151], v[184:187], v[104:107]
	v_mfma_f32_16x16x32_bf16 v[100:103], v[168:171], v[184:187], v[100:103]
	v_mfma_f32_16x16x32_bf16 v[88:91], v[148:151], v[210:213], v[88:91]
	v_mfma_f32_16x16x32_bf16 v[84:87], v[168:171], v[210:213], v[84:87]
	v_mfma_f32_16x16x32_bf16 v[72:75], v[148:151], v[238:241], v[72:75]
	v_mfma_f32_16x16x32_bf16 v[68:71], v[168:171], v[238:241], v[68:71]
	v_mfma_f32_16x16x32_bf16 v[120:123], v[152:155], v[180:183], v[120:123]
	v_mfma_f32_16x16x32_bf16 v[116:119], v[172:175], v[180:183], v[116:119]
	v_mfma_f32_16x16x32_bf16 v[104:107], v[152:155], v[192:195], v[104:107]
	v_mfma_f32_16x16x32_bf16 v[100:103], v[172:175], v[192:195], v[100:103]
	v_mfma_f32_16x16x32_bf16 v[88:91], v[152:155], v[234:237], v[88:91]
	v_mfma_f32_16x16x32_bf16 v[84:87], v[172:175], v[234:237], v[84:87]
	v_mfma_f32_16x16x32_bf16 v[72:75], v[152:155], v[242:245], v[72:75]
	v_mfma_f32_16x16x32_bf16 v[68:71], v[172:175], v[242:245], v[68:71]
	s_barrier
	s_add_u32 s34, s64, 0x8000
	s_addc_u32 s35, s65, 0
	s_add_i32 s55, s55, s0
	s_mov_b32 m0, s55
	ds_read_b128 v[176:179], v189 offset:49152
	ds_read_b128 v[180:183], v189 offset:50176
	ds_read_b128 v[184:187], v189 offset:51200
	ds_read_b128 v[192:195], v189 offset:52224
	ds_read_b128 v[210:213], v189 offset:53248
	ds_read_b128 v[234:237], v189 offset:54272
	ds_read_b128 v[238:241], v189 offset:55296
	ds_read_b128 v[242:245], v189 offset:56320
	global_load_lds_dwordx4 v156, s[34:35]
	s_add_i32 m0, s55, 0x2000
	s_mov_b64 s[100:101], s[34:35]
	s_add_u32 s34, s64, 0xc000
	s_addc_u32 s35, s65, 0
	s_add_i32 s55, s58, s0
	global_load_lds_dwordx4 v160, s[100:101]
	s_mov_b32 m0, s55
	s_nop 0
	global_load_lds_dwordx4 v156, s[34:35]
	s_add_i32 m0, s55, 0x2000
	s_nop 0
	global_load_lds_dwordx4 v160, s[34:35]
	s_mov_b32 m0, s91
	s_nop 0
	s_add_u32 s100, s66, s92
	s_addc_u32 s101, s67, s93
	global_load_lds_dwordx4 v158, s[100:101]
	s_mov_b32 m0, s30
	s_nop 0
	s_add_u32 s100, s66, s92
	s_addc_u32 s101, s67, s93
	global_load_lds_dwordx4 v162, s[100:101]
	s_waitcnt vmcnt(8) lgkmcnt(0)
	s_barrier
	v_mfma_f32_16x16x32_bf16 v[64:67], v[132:135], v[176:179], v[64:67]
	v_mfma_f32_16x16x32_bf16 v[60:63], v[140:143], v[176:179], v[60:63]
	v_mfma_f32_16x16x32_bf16 v[48:51], v[132:135], v[184:187], v[48:51]
	v_mfma_f32_16x16x32_bf16 v[44:47], v[140:143], v[184:187], v[44:47]
	v_mfma_f32_16x16x32_bf16 v[30:33], v[132:135], v[210:213], v[30:33]
	v_mfma_f32_16x16x32_bf16 v[26:29], v[140:143], v[210:213], v[26:29]
	v_mfma_f32_16x16x32_bf16 v[14:17], v[132:135], v[238:241], v[14:17]
	v_mfma_f32_16x16x32_bf16 v[10:13], v[140:143], v[238:241], v[10:13]
	v_mfma_f32_16x16x32_bf16 v[64:67], v[136:139], v[180:183], v[64:67]
	v_mfma_f32_16x16x32_bf16 v[60:63], v[144:147], v[180:183], v[60:63]
	v_mfma_f32_16x16x32_bf16 v[48:51], v[136:139], v[192:195], v[48:51]
	v_mfma_f32_16x16x32_bf16 v[44:47], v[144:147], v[192:195], v[44:47]
	v_mfma_f32_16x16x32_bf16 v[30:33], v[136:139], v[234:237], v[30:33]
	v_mfma_f32_16x16x32_bf16 v[26:29], v[144:147], v[234:237], v[26:29]
	v_mfma_f32_16x16x32_bf16 v[14:17], v[136:139], v[242:245], v[14:17]
	v_mfma_f32_16x16x32_bf16 v[10:13], v[144:147], v[242:245], v[10:13]
	v_mfma_f32_16x16x32_bf16 v[56:59], v[148:151], v[176:179], v[56:59]
	v_mfma_f32_16x16x32_bf16 v[52:55], v[168:171], v[176:179], v[52:55]
	v_mfma_f32_16x16x32_bf16 v[40:43], v[148:151], v[184:187], v[40:43]
	v_mfma_f32_16x16x32_bf16 v[36:39], v[168:171], v[184:187], v[36:39]
	v_mfma_f32_16x16x32_bf16 v[22:25], v[148:151], v[210:213], v[22:25]
	v_mfma_f32_16x16x32_bf16 v[18:21], v[168:171], v[210:213], v[18:21]
	v_mfma_f32_16x16x32_bf16 v[6:9], v[148:151], v[238:241], v[6:9]
	v_mfma_f32_16x16x32_bf16 v[2:5], v[168:171], v[238:241], v[2:5]
	v_mfma_f32_16x16x32_bf16 v[56:59], v[152:155], v[180:183], v[56:59]
	v_mfma_f32_16x16x32_bf16 v[52:55], v[172:175], v[180:183], v[52:55]
	v_mfma_f32_16x16x32_bf16 v[40:43], v[152:155], v[192:195], v[40:43]
	v_mfma_f32_16x16x32_bf16 v[36:39], v[172:175], v[192:195], v[36:39]
	v_mfma_f32_16x16x32_bf16 v[22:25], v[152:155], v[234:237], v[22:25]
	v_mfma_f32_16x16x32_bf16 v[18:21], v[172:175], v[234:237], v[18:21]
	v_mfma_f32_16x16x32_bf16 v[6:9], v[152:155], v[242:245], v[6:9]
	v_mfma_f32_16x16x32_bf16 v[2:5], v[172:175], v[242:245], v[2:5]
	s_barrier
	s_add_i32 s49, s49, 2
	s_add_u32 s13, s13, 0x10000
	s_addc_u32 s28, s28, 0
	s_cmp_gt_u32 s49, 61
	s_mov_b64 s[60:61], s[62:63]
	s_cbranch_scc0 .LBB0_877
	s_and_b64 vcc, exec, s[46:47]
	s_cbranch_vccz .LBB0_880
	s_barrier

.LBB0_1070:
	s_add_u32 s34, s12, 0xfff00080
	s_addc_u32 s35, s13, -1
	s_add_i32 s48, 0, 0x10000
	s_cmp_eq_u32 s59, 28
	s_cselect_b32 s67, s61, s35
	s_cselect_b32 s66, s60, s34
	s_cselect_b32 s65, s63, s58
	s_cselect_b32 s64, s62, s28
	s_add_i32 s49, 0, 0x14000
	ds_read_b128 v[100:103], v2 offset:0
	ds_read_b128 v[112:115], v2 offset:1024
	ds_read_b128 v[172:175], v2 offset:2048
	ds_read_b128 v[188:191], v2 offset:3072
	ds_read_b128 v[192:195], v2 offset:16384
	ds_read_b128 v[200:203], v2 offset:17408
	ds_read_b128 v[204:207], v2 offset:18432
	ds_read_b128 v[210:213], v2 offset:19456
	s_add_i32 m0, s29, 0xc000
	ds_read_b128 v[216:219], v197
	ds_read_b128 v[220:223], v197 offset:1024
	ds_read_b128 v[224:227], v197 offset:2048
	ds_read_b128 v[228:231], v197 offset:3072
	ds_read_b128 v[232:235], v197 offset:4096
	ds_read_b128 v[236:239], v197 offset:5120
	ds_read_b128 v[240:243], v197 offset:6144
	ds_read_b128 v[244:247], v197 offset:7168
	global_load_lds_dwordx4 v184, s[12:13]
	s_add_i32 m0, s29, 0xe000
	s_nop 0
	global_load_lds_dwordx4 v186, s[12:13]
	s_waitcnt vmcnt(8) lgkmcnt(0)
	s_barrier
	v_mfma_i32_16x16x64_i8 v[168:171], v[100:103], v[216:219], v[168:171]
	v_mfma_i32_16x16x64_i8 v[160:163], v[172:175], v[216:219], v[160:163]
	v_mfma_i32_16x16x64_i8 v[152:155], v[100:103], v[224:227], v[152:155]
	v_mfma_i32_16x16x64_i8 v[144:147], v[172:175], v[224:227], v[144:147]
	v_mfma_i32_16x16x64_i8 v[136:139], v[100:103], v[232:235], v[136:139]
	v_mfma_i32_16x16x64_i8 v[128:131], v[172:175], v[232:235], v[128:131]
	v_mfma_i32_16x16x64_i8 v[120:123], v[100:103], v[240:243], v[120:123]
	v_mfma_i32_16x16x64_i8 v[108:111], v[172:175], v[240:243], v[108:111]
	v_mfma_i32_16x16x64_i8 v[168:171], v[112:115], v[220:223], v[168:171]
	v_mfma_i32_16x16x64_i8 v[160:163], v[188:191], v[220:223], v[160:163]
	v_mfma_i32_16x16x64_i8 v[152:155], v[112:115], v[228:231], v[152:155]
	v_mfma_i32_16x16x64_i8 v[144:147], v[188:191], v[228:231], v[144:147]
	v_mfma_i32_16x16x64_i8 v[136:139], v[112:115], v[236:239], v[136:139]
	v_mfma_i32_16x16x64_i8 v[128:131], v[188:191], v[236:239], v[128:131]
	v_mfma_i32_16x16x64_i8 v[120:123], v[112:115], v[244:247], v[120:123]
	v_mfma_i32_16x16x64_i8 v[108:111], v[188:191], v[244:247], v[108:111]
	v_mfma_i32_16x16x64_i8 v[164:167], v[192:195], v[216:219], v[164:167]
	v_mfma_i32_16x16x64_i8 v[156:159], v[204:207], v[216:219], v[156:159]
	v_mfma_i32_16x16x64_i8 v[148:151], v[192:195], v[224:227], v[148:151]
	v_mfma_i32_16x16x64_i8 v[140:143], v[204:207], v[224:227], v[140:143]
	v_mfma_i32_16x16x64_i8 v[132:135], v[192:195], v[232:235], v[132:135]
	v_mfma_i32_16x16x64_i8 v[124:127], v[204:207], v[232:235], v[124:127]
	v_mfma_i32_16x16x64_i8 v[116:119], v[192:195], v[240:243], v[116:119]
	v_mfma_i32_16x16x64_i8 v[104:107], v[204:207], v[240:243], v[104:107]
	v_mfma_i32_16x16x64_i8 v[164:167], v[200:203], v[220:223], v[164:167]
	v_mfma_i32_16x16x64_i8 v[156:159], v[210:213], v[220:223], v[156:159]
	v_mfma_i32_16x16x64_i8 v[148:151], v[200:203], v[228:231], v[148:151]
	v_mfma_i32_16x16x64_i8 v[140:143], v[210:213], v[228:231], v[140:143]
	v_mfma_i32_16x16x64_i8 v[132:135], v[200:203], v[236:239], v[132:135]
	v_mfma_i32_16x16x64_i8 v[124:127], v[210:213], v[236:239], v[124:127]
	v_mfma_i32_16x16x64_i8 v[116:119], v[200:203], v[244:247], v[116:119]
	v_mfma_i32_16x16x64_i8 v[104:107], v[210:213], v[244:247], v[104:107]
	s_barrier
	s_add_i32 s34, s48, s0
	s_mov_b32 m0, s34
	ds_read_b128 v[216:219], v197 offset:16384
	ds_read_b128 v[220:223], v197 offset:17408
	ds_read_b128 v[224:227], v197 offset:18432
	ds_read_b128 v[228:231], v197 offset:19456
	ds_read_b128 v[232:235], v197 offset:20480
	ds_read_b128 v[236:239], v197 offset:21504
	ds_read_b128 v[240:243], v197 offset:22528
	ds_read_b128 v[244:247], v197 offset:23552
	global_load_lds_dwordx4 v176, s[64:65]
	s_add_i32 m0, s34, 0x2000
	s_add_u32 s34, s64, 0x4000
	s_addc_u32 s35, s65, 0
	s_add_i32 s48, s49, s0
	global_load_lds_dwordx4 v180, s[64:65]
	s_mov_b32 m0, s48
	s_nop 0
	global_load_lds_dwordx4 v176, s[34:35]
	s_add_i32 m0, s48, 0x2000
	s_nop 0
	global_load_lds_dwordx4 v180, s[34:35]
	s_mov_b32 m0, s29
	s_nop 0
	global_load_lds_dwordx4 v178, s[66:67]
	s_mov_b32 m0, s45
	s_nop 0
	global_load_lds_dwordx4 v182, s[66:67]
	s_waitcnt vmcnt(8) lgkmcnt(0)
	s_barrier
	v_mfma_i32_16x16x64_i8 v[96:99], v[100:103], v[216:219], v[96:99]
	v_mfma_i32_16x16x64_i8 v[88:91], v[172:175], v[216:219], v[88:91]
	v_mfma_i32_16x16x64_i8 v[80:83], v[100:103], v[224:227], v[80:83]
	v_mfma_i32_16x16x64_i8 v[72:75], v[172:175], v[224:227], v[72:75]
	v_mfma_i32_16x16x64_i8 v[64:67], v[100:103], v[232:235], v[64:67]
	v_mfma_i32_16x16x64_i8 v[56:59], v[172:175], v[232:235], v[56:59]
	v_mfma_i32_16x16x64_i8 v[48:51], v[100:103], v[240:243], v[48:51]
	v_mfma_i32_16x16x64_i8 v[40:43], v[172:175], v[240:243], v[40:43]
	v_mfma_i32_16x16x64_i8 v[96:99], v[112:115], v[220:223], v[96:99]
	v_mfma_i32_16x16x64_i8 v[88:91], v[188:191], v[220:223], v[88:91]
	v_mfma_i32_16x16x64_i8 v[80:83], v[112:115], v[228:231], v[80:83]
	v_mfma_i32_16x16x64_i8 v[72:75], v[188:191], v[228:231], v[72:75]
	v_mfma_i32_16x16x64_i8 v[64:67], v[112:115], v[236:239], v[64:67]
	v_mfma_i32_16x16x64_i8 v[56:59], v[188:191], v[236:239], v[56:59]
	v_mfma_i32_16x16x64_i8 v[48:51], v[112:115], v[244:247], v[48:51]
	v_mfma_i32_16x16x64_i8 v[40:43], v[188:191], v[244:247], v[40:43]
	v_mfma_i32_16x16x64_i8 v[92:95], v[192:195], v[216:219], v[92:95]
	v_mfma_i32_16x16x64_i8 v[84:87], v[204:207], v[216:219], v[84:87]
	v_mfma_i32_16x16x64_i8 v[76:79], v[192:195], v[224:227], v[76:79]
	v_mfma_i32_16x16x64_i8 v[68:71], v[204:207], v[224:227], v[68:71]
	v_mfma_i32_16x16x64_i8 v[60:63], v[192:195], v[232:235], v[60:63]
	v_mfma_i32_16x16x64_i8 v[52:55], v[204:207], v[232:235], v[52:55]
	v_mfma_i32_16x16x64_i8 v[44:47], v[192:195], v[240:243], v[44:47]
	v_mfma_i32_16x16x64_i8 v[36:39], v[204:207], v[240:243], v[36:39]
	v_mfma_i32_16x16x64_i8 v[92:95], v[200:203], v[220:223], v[92:95]
	v_mfma_i32_16x16x64_i8 v[84:87], v[210:213], v[220:223], v[84:87]
	v_mfma_i32_16x16x64_i8 v[76:79], v[200:203], v[228:231], v[76:79]
	v_mfma_i32_16x16x64_i8 v[68:71], v[210:213], v[228:231], v[68:71]
	v_mfma_i32_16x16x64_i8 v[60:63], v[200:203], v[236:239], v[60:63]
	v_mfma_i32_16x16x64_i8 v[52:55], v[210:213], v[236:239], v[52:55]
	v_mfma_i32_16x16x64_i8 v[44:47], v[200:203], v[244:247], v[44:47]
	v_mfma_i32_16x16x64_i8 v[36:39], v[210:213], v[244:247], v[36:39]
	s_barrier
	s_add_i32 s48, 0, 0x18000
	s_add_i32 s49, 0, 0x1c000
	ds_read_b128 v[100:103], v2 offset:32768
	ds_read_b128 v[112:115], v2 offset:33792
	ds_read_b128 v[172:175], v2 offset:34816
	ds_read_b128 v[188:191], v2 offset:35840
	ds_read_b128 v[192:195], v2 offset:49152
	ds_read_b128 v[200:203], v2 offset:50176
	ds_read_b128 v[204:207], v2 offset:51200
	ds_read_b128 v[210:213], v2 offset:52224
	s_add_u32 s34, s66, 0x100000
	s_addc_u32 s35, s67, 0
	s_mov_b32 m0, s82
	ds_read_b128 v[216:219], v197 offset:32768
	ds_read_b128 v[220:223], v197 offset:33792
	ds_read_b128 v[224:227], v197 offset:34816
	ds_read_b128 v[228:231], v197 offset:35840
	ds_read_b128 v[232:235], v197 offset:36864
	ds_read_b128 v[236:239], v197 offset:37888
	ds_read_b128 v[240:243], v197 offset:38912
	ds_read_b128 v[244:247], v197 offset:39936
	global_load_lds_dwordx4 v178, s[34:35]
	s_mov_b32 m0, s90
	s_nop 0
	global_load_lds_dwordx4 v182, s[34:35]
	s_waitcnt vmcnt(8) lgkmcnt(0)
	s_barrier
	v_mfma_i32_16x16x64_i8 v[168:171], v[100:103], v[216:219], v[168:171]
	v_mfma_i32_16x16x64_i8 v[160:163], v[172:175], v[216:219], v[160:163]
	v_mfma_i32_16x16x64_i8 v[152:155], v[100:103], v[224:227], v[152:155]
	v_mfma_i32_16x16x64_i8 v[144:147], v[172:175], v[224:227], v[144:147]
	v_mfma_i32_16x16x64_i8 v[136:139], v[100:103], v[232:235], v[136:139]
	v_mfma_i32_16x16x64_i8 v[128:131], v[172:175], v[232:235], v[128:131]
	v_mfma_i32_16x16x64_i8 v[120:123], v[100:103], v[240:243], v[120:123]
	v_mfma_i32_16x16x64_i8 v[108:111], v[172:175], v[240:243], v[108:111]
	v_mfma_i32_16x16x64_i8 v[168:171], v[112:115], v[220:223], v[168:171]
	v_mfma_i32_16x16x64_i8 v[160:163], v[188:191], v[220:223], v[160:163]
	v_mfma_i32_16x16x64_i8 v[152:155], v[112:115], v[228:231], v[152:155]
	v_mfma_i32_16x16x64_i8 v[144:147], v[188:191], v[228:231], v[144:147]
	v_mfma_i32_16x16x64_i8 v[136:139], v[112:115], v[236:239], v[136:139]
	v_mfma_i32_16x16x64_i8 v[128:131], v[188:191], v[236:239], v[128:131]
	v_mfma_i32_16x16x64_i8 v[120:123], v[112:115], v[244:247], v[120:123]
	v_mfma_i32_16x16x64_i8 v[108:111], v[188:191], v[244:247], v[108:111]
	v_mfma_i32_16x16x64_i8 v[164:167], v[192:195], v[216:219], v[164:167]
	v_mfma_i32_16x16x64_i8 v[156:159], v[204:207], v[216:219], v[156:159]
	v_mfma_i32_16x16x64_i8 v[148:151], v[192:195], v[224:227], v[148:151]
	v_mfma_i32_16x16x64_i8 v[140:143], v[204:207], v[224:227], v[140:143]
	v_mfma_i32_16x16x64_i8 v[132:135], v[192:195], v[232:235], v[132:135]
	v_mfma_i32_16x16x64_i8 v[124:127], v[204:207], v[232:235], v[124:127]
	v_mfma_i32_16x16x64_i8 v[116:119], v[192:195], v[240:243], v[116:119]
	v_mfma_i32_16x16x64_i8 v[104:107], v[204:207], v[240:243], v[104:107]
	v_mfma_i32_16x16x64_i8 v[164:167], v[200:203], v[220:223], v[164:167]
	v_mfma_i32_16x16x64_i8 v[156:159], v[210:213], v[220:223], v[156:159]
	v_mfma_i32_16x16x64_i8 v[148:151], v[200:203], v[228:231], v[148:151]
	v_mfma_i32_16x16x64_i8 v[140:143], v[210:213], v[228:231], v[140:143]
	v_mfma_i32_16x16x64_i8 v[132:135], v[200:203], v[236:239], v[132:135]
	v_mfma_i32_16x16x64_i8 v[124:127], v[210:213], v[236:239], v[124:127]
	v_mfma_i32_16x16x64_i8 v[116:119], v[200:203], v[244:247], v[116:119]
	v_mfma_i32_16x16x64_i8 v[104:107], v[210:213], v[244:247], v[104:107]
	s_barrier
	s_add_u32 s34, s64, 0x8000
	s_addc_u32 s35, s65, 0
	s_add_i32 s48, s48, s0
	s_mov_b32 m0, s48
	ds_read_b128 v[216:219], v197 offset:49152
	ds_read_b128 v[220:223], v197 offset:50176
	ds_read_b128 v[224:227], v197 offset:51200
	ds_read_b128 v[228:231], v197 offset:52224
	ds_read_b128 v[232:235], v197 offset:53248
	ds_read_b128 v[236:239], v197 offset:54272
	ds_read_b128 v[240:243], v197 offset:55296
	ds_read_b128 v[244:247], v197 offset:56320
	global_load_lds_dwordx4 v176, s[34:35]
	s_add_i32 m0, s48, 0x2000
	s_mov_b64 s[100:101], s[34:35]
	s_add_u32 s34, s64, 0xc000
	s_addc_u32 s35, s65, 0
	s_add_i32 s48, s49, s0
	global_load_lds_dwordx4 v180, s[100:101]
	s_mov_b32 m0, s48
	s_nop 0
	global_load_lds_dwordx4 v176, s[34:35]
	s_add_i32 m0, s48, 0x2000
	s_nop 0
	global_load_lds_dwordx4 v180, s[34:35]
	s_mov_b32 m0, s91
	s_nop 0
	s_add_u32 s100, s66, s92
	s_addc_u32 s101, s67, s93
	global_load_lds_dwordx4 v178, s[100:101]
	s_mov_b32 m0, s30
	s_nop 0
	s_add_u32 s100, s66, s92
	s_addc_u32 s101, s67, s93
	global_load_lds_dwordx4 v182, s[100:101]
	s_waitcnt vmcnt(8) lgkmcnt(0)
	s_barrier
	v_mfma_i32_16x16x64_i8 v[96:99], v[100:103], v[216:219], v[96:99]
	v_mfma_i32_16x16x64_i8 v[88:91], v[172:175], v[216:219], v[88:91]
	v_mfma_i32_16x16x64_i8 v[80:83], v[100:103], v[224:227], v[80:83]
	v_mfma_i32_16x16x64_i8 v[72:75], v[172:175], v[224:227], v[72:75]
	v_mfma_i32_16x16x64_i8 v[64:67], v[100:103], v[232:235], v[64:67]
	v_mfma_i32_16x16x64_i8 v[56:59], v[172:175], v[232:235], v[56:59]
	v_mfma_i32_16x16x64_i8 v[48:51], v[100:103], v[240:243], v[48:51]
	v_mfma_i32_16x16x64_i8 v[40:43], v[172:175], v[240:243], v[40:43]
	v_mfma_i32_16x16x64_i8 v[96:99], v[112:115], v[220:223], v[96:99]
	v_mfma_i32_16x16x64_i8 v[88:91], v[188:191], v[220:223], v[88:91]
	v_mfma_i32_16x16x64_i8 v[80:83], v[112:115], v[228:231], v[80:83]
	v_mfma_i32_16x16x64_i8 v[72:75], v[188:191], v[228:231], v[72:75]
	v_mfma_i32_16x16x64_i8 v[64:67], v[112:115], v[236:239], v[64:67]
	v_mfma_i32_16x16x64_i8 v[56:59], v[188:191], v[236:239], v[56:59]
	v_mfma_i32_16x16x64_i8 v[48:51], v[112:115], v[244:247], v[48:51]
	v_mfma_i32_16x16x64_i8 v[40:43], v[188:191], v[244:247], v[40:43]
	v_mfma_i32_16x16x64_i8 v[92:95], v[192:195], v[216:219], v[92:95]
	v_mfma_i32_16x16x64_i8 v[84:87], v[204:207], v[216:219], v[84:87]
	v_mfma_i32_16x16x64_i8 v[76:79], v[192:195], v[224:227], v[76:79]
	v_mfma_i32_16x16x64_i8 v[68:71], v[204:207], v[224:227], v[68:71]
	v_mfma_i32_16x16x64_i8 v[60:63], v[192:195], v[232:235], v[60:63]
	v_mfma_i32_16x16x64_i8 v[52:55], v[204:207], v[232:235], v[52:55]
	v_mfma_i32_16x16x64_i8 v[44:47], v[192:195], v[240:243], v[44:47]
	v_mfma_i32_16x16x64_i8 v[36:39], v[204:207], v[240:243], v[36:39]
	v_mfma_i32_16x16x64_i8 v[92:95], v[200:203], v[220:223], v[92:95]
	v_mfma_i32_16x16x64_i8 v[84:87], v[210:213], v[220:223], v[84:87]
	v_mfma_i32_16x16x64_i8 v[76:79], v[200:203], v[228:231], v[76:79]
	v_mfma_i32_16x16x64_i8 v[68:71], v[210:213], v[228:231], v[68:71]
	v_mfma_i32_16x16x64_i8 v[60:63], v[200:203], v[236:239], v[60:63]
	v_mfma_i32_16x16x64_i8 v[52:55], v[210:213], v[236:239], v[52:55]
	v_mfma_i32_16x16x64_i8 v[44:47], v[200:203], v[244:247], v[44:47]
	v_mfma_i32_16x16x64_i8 v[36:39], v[210:213], v[244:247], v[36:39]
	s_barrier
	s_add_i32 s59, s59, 2
	s_add_u32 s28, s28, 0x10000
	s_addc_u32 s58, s58, 0
	s_add_u32 s12, s12, 0x100
	s_addc_u32 s13, s13, 0
	s_cmp_gt_u32 s59, 29
	s_cbranch_scc0 .LBB0_1070
	s_and_b64 vcc, exec, s[46:47]
	s_cbranch_vccz .LBB0_1073
	s_barrier

.LBB0_1261:
	s_add_u32 s42, s22, 0x100
	s_addc_u32 s43, s23, 0
	s_add_i32 s34, 0, 0x10000
	s_cmpk_eq_i32 s60, 0xa8
	s_cselect_b32 s51, s19, s43
	s_cselect_b32 s50, s18, s42
	s_cselect_b32 s49, s21, s59
	s_cselect_b32 s48, s20, s58
	s_add_i32 s35, 0, 0x14000
	ds_read_b128 v[132:135], v188 offset:0
	ds_read_b128 v[136:139], v188 offset:1024
	ds_read_b128 v[140:143], v188 offset:2048
	ds_read_b128 v[144:147], v188 offset:3072
	ds_read_b128 v[148:151], v188 offset:16384
	ds_read_b128 v[152:155], v188 offset:17408
	ds_read_b128 v[168:171], v188 offset:18432
	ds_read_b128 v[172:175], v188 offset:19456
	s_add_i32 m0, s29, 0xc000
	ds_read_b128 v[176:179], v187
	ds_read_b128 v[180:183], v187 offset:1024
	ds_read_b128 v[192:195], v187 offset:2048
	ds_read_b128 v[210:213], v187 offset:3072
	ds_read_b128 v[232:235], v187 offset:4096
	ds_read_b128 v[236:239], v187 offset:5120
	ds_read_b128 v[240:243], v187 offset:6144
	ds_read_b128 v[244:247], v187 offset:7168
	global_load_lds_dwordx4 v164, s[22:23]
	s_add_i32 m0, s29, 0xe000
	s_nop 0
	global_load_lds_dwordx4 v166, s[22:23]
	s_waitcnt vmcnt(8) lgkmcnt(0)
	s_barrier
	v_mfma_f32_16x16x32_bf16 v[128:131], v[132:135], v[176:179], v[128:131]
	v_mfma_f32_16x16x32_bf16 v[124:127], v[140:143], v[176:179], v[124:127]
	v_mfma_f32_16x16x32_bf16 v[112:115], v[132:135], v[192:195], v[112:115]
	v_mfma_f32_16x16x32_bf16 v[108:111], v[140:143], v[192:195], v[108:111]
	v_mfma_f32_16x16x32_bf16 v[96:99], v[132:135], v[232:235], v[96:99]
	v_mfma_f32_16x16x32_bf16 v[92:95], v[140:143], v[232:235], v[92:95]
	v_mfma_f32_16x16x32_bf16 v[80:83], v[132:135], v[240:243], v[80:83]
	v_mfma_f32_16x16x32_bf16 v[76:79], v[140:143], v[240:243], v[76:79]
	v_mfma_f32_16x16x32_bf16 v[128:131], v[136:139], v[180:183], v[128:131]
	v_mfma_f32_16x16x32_bf16 v[124:127], v[144:147], v[180:183], v[124:127]
	v_mfma_f32_16x16x32_bf16 v[112:115], v[136:139], v[210:213], v[112:115]
	v_mfma_f32_16x16x32_bf16 v[108:111], v[144:147], v[210:213], v[108:111]
	v_mfma_f32_16x16x32_bf16 v[96:99], v[136:139], v[236:239], v[96:99]
	v_mfma_f32_16x16x32_bf16 v[92:95], v[144:147], v[236:239], v[92:95]
	v_mfma_f32_16x16x32_bf16 v[80:83], v[136:139], v[244:247], v[80:83]
	v_mfma_f32_16x16x32_bf16 v[76:79], v[144:147], v[244:247], v[76:79]
	v_mfma_f32_16x16x32_bf16 v[120:123], v[148:151], v[176:179], v[120:123]
	v_mfma_f32_16x16x32_bf16 v[116:119], v[168:171], v[176:179], v[116:119]
	v_mfma_f32_16x16x32_bf16 v[104:107], v[148:151], v[192:195], v[104:107]
	v_mfma_f32_16x16x32_bf16 v[100:103], v[168:171], v[192:195], v[100:103]
	v_mfma_f32_16x16x32_bf16 v[88:91], v[148:151], v[232:235], v[88:91]
	v_mfma_f32_16x16x32_bf16 v[84:87], v[168:171], v[232:235], v[84:87]
	v_mfma_f32_16x16x32_bf16 v[72:75], v[148:151], v[240:243], v[72:75]
	v_mfma_f32_16x16x32_bf16 v[68:71], v[168:171], v[240:243], v[68:71]
	v_mfma_f32_16x16x32_bf16 v[120:123], v[152:155], v[180:183], v[120:123]
	v_mfma_f32_16x16x32_bf16 v[116:119], v[172:175], v[180:183], v[116:119]
	v_mfma_f32_16x16x32_bf16 v[104:107], v[152:155], v[210:213], v[104:107]
	v_mfma_f32_16x16x32_bf16 v[100:103], v[172:175], v[210:213], v[100:103]
	v_mfma_f32_16x16x32_bf16 v[88:91], v[152:155], v[236:239], v[88:91]
	v_mfma_f32_16x16x32_bf16 v[84:87], v[172:175], v[236:239], v[84:87]
	v_mfma_f32_16x16x32_bf16 v[72:75], v[152:155], v[244:247], v[72:75]
	v_mfma_f32_16x16x32_bf16 v[68:71], v[172:175], v[244:247], v[68:71]
	s_barrier
	s_add_i32 s22, s34, s0
	s_mov_b32 m0, s22
	ds_read_b128 v[176:179], v187 offset:16384
	ds_read_b128 v[180:183], v187 offset:17408
	ds_read_b128 v[192:195], v187 offset:18432
	ds_read_b128 v[210:213], v187 offset:19456
	ds_read_b128 v[232:235], v187 offset:20480
	ds_read_b128 v[236:239], v187 offset:21504
	ds_read_b128 v[240:243], v187 offset:22528
	ds_read_b128 v[244:247], v187 offset:23552
	global_load_lds_dwordx4 v156, s[48:49]
	s_add_i32 m0, s22, 0x2000
	s_add_u32 s22, s48, 0x4000
	s_addc_u32 s23, s49, 0
	s_add_i32 s34, s35, s0
	global_load_lds_dwordx4 v160, s[48:49]
	s_mov_b32 m0, s34
	s_nop 0
	global_load_lds_dwordx4 v156, s[22:23]
	s_add_i32 m0, s34, 0x2000
	s_nop 0
	global_load_lds_dwordx4 v160, s[22:23]
	s_mov_b32 m0, s29
	s_nop 0
	global_load_lds_dwordx4 v158, s[50:51]
	s_mov_b32 m0, s45
	s_nop 0
	global_load_lds_dwordx4 v162, s[50:51]
	s_waitcnt vmcnt(8) lgkmcnt(0)
	s_barrier
	v_mfma_f32_16x16x32_bf16 v[64:67], v[132:135], v[176:179], v[64:67]
	v_mfma_f32_16x16x32_bf16 v[60:63], v[140:143], v[176:179], v[60:63]
	v_mfma_f32_16x16x32_bf16 v[48:51], v[132:135], v[192:195], v[48:51]
	v_mfma_f32_16x16x32_bf16 v[44:47], v[140:143], v[192:195], v[44:47]
	v_mfma_f32_16x16x32_bf16 v[30:33], v[132:135], v[232:235], v[30:33]
	v_mfma_f32_16x16x32_bf16 v[26:29], v[140:143], v[232:235], v[26:29]
	v_mfma_f32_16x16x32_bf16 v[14:17], v[132:135], v[240:243], v[14:17]
	v_mfma_f32_16x16x32_bf16 v[10:13], v[140:143], v[240:243], v[10:13]
	v_mfma_f32_16x16x32_bf16 v[64:67], v[136:139], v[180:183], v[64:67]
	v_mfma_f32_16x16x32_bf16 v[60:63], v[144:147], v[180:183], v[60:63]
	v_mfma_f32_16x16x32_bf16 v[48:51], v[136:139], v[210:213], v[48:51]
	v_mfma_f32_16x16x32_bf16 v[44:47], v[144:147], v[210:213], v[44:47]
	v_mfma_f32_16x16x32_bf16 v[30:33], v[136:139], v[236:239], v[30:33]
	v_mfma_f32_16x16x32_bf16 v[26:29], v[144:147], v[236:239], v[26:29]
	v_mfma_f32_16x16x32_bf16 v[14:17], v[136:139], v[244:247], v[14:17]
	v_mfma_f32_16x16x32_bf16 v[10:13], v[144:147], v[244:247], v[10:13]
	v_mfma_f32_16x16x32_bf16 v[56:59], v[148:151], v[176:179], v[56:59]
	v_mfma_f32_16x16x32_bf16 v[52:55], v[168:171], v[176:179], v[52:55]
	v_mfma_f32_16x16x32_bf16 v[40:43], v[148:151], v[192:195], v[40:43]
	v_mfma_f32_16x16x32_bf16 v[36:39], v[168:171], v[192:195], v[36:39]
	v_mfma_f32_16x16x32_bf16 v[22:25], v[148:151], v[232:235], v[22:25]
	v_mfma_f32_16x16x32_bf16 v[18:21], v[168:171], v[232:235], v[18:21]
	v_mfma_f32_16x16x32_bf16 v[6:9], v[148:151], v[240:243], v[6:9]
	v_mfma_f32_16x16x32_bf16 v[2:5], v[168:171], v[240:243], v[2:5]
	v_mfma_f32_16x16x32_bf16 v[56:59], v[152:155], v[180:183], v[56:59]
	v_mfma_f32_16x16x32_bf16 v[52:55], v[172:175], v[180:183], v[52:55]
	v_mfma_f32_16x16x32_bf16 v[40:43], v[152:155], v[210:213], v[40:43]
	v_mfma_f32_16x16x32_bf16 v[36:39], v[172:175], v[210:213], v[36:39]
	v_mfma_f32_16x16x32_bf16 v[22:25], v[152:155], v[236:239], v[22:25]
	v_mfma_f32_16x16x32_bf16 v[18:21], v[172:175], v[236:239], v[18:21]
	v_mfma_f32_16x16x32_bf16 v[6:9], v[152:155], v[244:247], v[6:9]
	v_mfma_f32_16x16x32_bf16 v[2:5], v[172:175], v[244:247], v[2:5]
	s_barrier
	s_add_i32 s34, 0, 0x18000
	s_add_i32 s35, 0, 0x1c000
	ds_read_b128 v[132:135], v188 offset:32768
	ds_read_b128 v[136:139], v188 offset:33792
	ds_read_b128 v[140:143], v188 offset:34816
	ds_read_b128 v[144:147], v188 offset:35840
	ds_read_b128 v[148:151], v188 offset:49152
	ds_read_b128 v[152:155], v188 offset:50176
	ds_read_b128 v[168:171], v188 offset:51200
	ds_read_b128 v[172:175], v188 offset:52224
	s_add_u32 s22, s50, 0x2b0000
	s_addc_u32 s23, s51, 0
	s_mov_b32 m0, s82
	ds_read_b128 v[176:179], v187 offset:32768
	ds_read_b128 v[180:183], v187 offset:33792
	ds_read_b128 v[192:195], v187 offset:34816
	ds_read_b128 v[210:213], v187 offset:35840
	ds_read_b128 v[232:235], v187 offset:36864
	ds_read_b128 v[236:239], v187 offset:37888
	ds_read_b128 v[240:243], v187 offset:38912
	ds_read_b128 v[244:247], v187 offset:39936
	global_load_lds_dwordx4 v158, s[22:23]
	s_mov_b32 m0, s90
	s_nop 0
	global_load_lds_dwordx4 v162, s[22:23]
	s_waitcnt vmcnt(8) lgkmcnt(0)
	s_barrier
	v_mfma_f32_16x16x32_bf16 v[128:131], v[132:135], v[176:179], v[128:131]
	v_mfma_f32_16x16x32_bf16 v[124:127], v[140:143], v[176:179], v[124:127]
	v_mfma_f32_16x16x32_bf16 v[112:115], v[132:135], v[192:195], v[112:115]
	v_mfma_f32_16x16x32_bf16 v[108:111], v[140:143], v[192:195], v[108:111]
	v_mfma_f32_16x16x32_bf16 v[96:99], v[132:135], v[232:235], v[96:99]
	v_mfma_f32_16x16x32_bf16 v[92:95], v[140:143], v[232:235], v[92:95]
	v_mfma_f32_16x16x32_bf16 v[80:83], v[132:135], v[240:243], v[80:83]
	v_mfma_f32_16x16x32_bf16 v[76:79], v[140:143], v[240:243], v[76:79]
	v_mfma_f32_16x16x32_bf16 v[128:131], v[136:139], v[180:183], v[128:131]
	v_mfma_f32_16x16x32_bf16 v[124:127], v[144:147], v[180:183], v[124:127]
	v_mfma_f32_16x16x32_bf16 v[112:115], v[136:139], v[210:213], v[112:115]
	v_mfma_f32_16x16x32_bf16 v[108:111], v[144:147], v[210:213], v[108:111]
	v_mfma_f32_16x16x32_bf16 v[96:99], v[136:139], v[236:239], v[96:99]
	v_mfma_f32_16x16x32_bf16 v[92:95], v[144:147], v[236:239], v[92:95]
	v_mfma_f32_16x16x32_bf16 v[80:83], v[136:139], v[244:247], v[80:83]
	v_mfma_f32_16x16x32_bf16 v[76:79], v[144:147], v[244:247], v[76:79]
	v_mfma_f32_16x16x32_bf16 v[120:123], v[148:151], v[176:179], v[120:123]
	v_mfma_f32_16x16x32_bf16 v[116:119], v[168:171], v[176:179], v[116:119]
	v_mfma_f32_16x16x32_bf16 v[104:107], v[148:151], v[192:195], v[104:107]
	v_mfma_f32_16x16x32_bf16 v[100:103], v[168:171], v[192:195], v[100:103]
	v_mfma_f32_16x16x32_bf16 v[88:91], v[148:151], v[232:235], v[88:91]
	v_mfma_f32_16x16x32_bf16 v[84:87], v[168:171], v[232:235], v[84:87]
	v_mfma_f32_16x16x32_bf16 v[72:75], v[148:151], v[240:243], v[72:75]
	v_mfma_f32_16x16x32_bf16 v[68:71], v[168:171], v[240:243], v[68:71]
	v_mfma_f32_16x16x32_bf16 v[120:123], v[152:155], v[180:183], v[120:123]
	v_mfma_f32_16x16x32_bf16 v[116:119], v[172:175], v[180:183], v[116:119]
	v_mfma_f32_16x16x32_bf16 v[104:107], v[152:155], v[210:213], v[104:107]
	v_mfma_f32_16x16x32_bf16 v[100:103], v[172:175], v[210:213], v[100:103]
	v_mfma_f32_16x16x32_bf16 v[88:91], v[152:155], v[236:239], v[88:91]
	v_mfma_f32_16x16x32_bf16 v[84:87], v[172:175], v[236:239], v[84:87]
	v_mfma_f32_16x16x32_bf16 v[72:75], v[152:155], v[244:247], v[72:75]
	v_mfma_f32_16x16x32_bf16 v[68:71], v[172:175], v[244:247], v[68:71]
	s_barrier
	s_add_u32 s22, s48, 0x8000
	s_addc_u32 s23, s49, 0
	s_add_i32 s34, s34, s0
	s_mov_b32 m0, s34
	ds_read_b128 v[176:179], v187 offset:49152
	ds_read_b128 v[180:183], v187 offset:50176
	ds_read_b128 v[192:195], v187 offset:51200
	ds_read_b128 v[210:213], v187 offset:52224
	ds_read_b128 v[232:235], v187 offset:53248
	ds_read_b128 v[236:239], v187 offset:54272
	ds_read_b128 v[240:243], v187 offset:55296
	ds_read_b128 v[244:247], v187 offset:56320
	global_load_lds_dwordx4 v156, s[22:23]
	s_add_i32 m0, s34, 0x2000
	s_mov_b64 s[100:101], s[22:23]
	s_add_u32 s22, s48, 0xc000
	s_addc_u32 s23, s49, 0
	s_add_i32 s34, s35, s0
	global_load_lds_dwordx4 v160, s[100:101]
	s_mov_b32 m0, s34
	s_nop 0
	global_load_lds_dwordx4 v156, s[22:23]
	s_add_i32 m0, s34, 0x2000
	s_nop 0
	global_load_lds_dwordx4 v160, s[22:23]
	s_mov_b32 m0, s91
	s_nop 0
	s_add_u32 s100, s50, s92
	s_addc_u32 s101, s51, s93
	global_load_lds_dwordx4 v158, s[100:101]
	s_mov_b32 m0, s30
	s_nop 0
	s_add_u32 s100, s50, s92
	s_addc_u32 s101, s51, s93
	global_load_lds_dwordx4 v162, s[100:101]
	s_waitcnt vmcnt(8) lgkmcnt(0)
	s_barrier
	v_mfma_f32_16x16x32_bf16 v[64:67], v[132:135], v[176:179], v[64:67]
	v_mfma_f32_16x16x32_bf16 v[60:63], v[140:143], v[176:179], v[60:63]
	v_mfma_f32_16x16x32_bf16 v[48:51], v[132:135], v[192:195], v[48:51]
	v_mfma_f32_16x16x32_bf16 v[44:47], v[140:143], v[192:195], v[44:47]
	v_mfma_f32_16x16x32_bf16 v[30:33], v[132:135], v[232:235], v[30:33]
	v_mfma_f32_16x16x32_bf16 v[26:29], v[140:143], v[232:235], v[26:29]
	v_mfma_f32_16x16x32_bf16 v[14:17], v[132:135], v[240:243], v[14:17]
	v_mfma_f32_16x16x32_bf16 v[10:13], v[140:143], v[240:243], v[10:13]
	v_mfma_f32_16x16x32_bf16 v[64:67], v[136:139], v[180:183], v[64:67]
	v_mfma_f32_16x16x32_bf16 v[60:63], v[144:147], v[180:183], v[60:63]
	v_mfma_f32_16x16x32_bf16 v[48:51], v[136:139], v[210:213], v[48:51]
	v_mfma_f32_16x16x32_bf16 v[44:47], v[144:147], v[210:213], v[44:47]
	v_mfma_f32_16x16x32_bf16 v[30:33], v[136:139], v[236:239], v[30:33]
	v_mfma_f32_16x16x32_bf16 v[26:29], v[144:147], v[236:239], v[26:29]
	v_mfma_f32_16x16x32_bf16 v[14:17], v[136:139], v[244:247], v[14:17]
	v_mfma_f32_16x16x32_bf16 v[10:13], v[144:147], v[244:247], v[10:13]
	v_mfma_f32_16x16x32_bf16 v[56:59], v[148:151], v[176:179], v[56:59]
	v_mfma_f32_16x16x32_bf16 v[52:55], v[168:171], v[176:179], v[52:55]
	v_mfma_f32_16x16x32_bf16 v[40:43], v[148:151], v[192:195], v[40:43]
	v_mfma_f32_16x16x32_bf16 v[36:39], v[168:171], v[192:195], v[36:39]
	v_mfma_f32_16x16x32_bf16 v[22:25], v[148:151], v[232:235], v[22:25]
	v_mfma_f32_16x16x32_bf16 v[18:21], v[168:171], v[232:235], v[18:21]
	v_mfma_f32_16x16x32_bf16 v[6:9], v[148:151], v[240:243], v[6:9]
	v_mfma_f32_16x16x32_bf16 v[2:5], v[168:171], v[240:243], v[2:5]
	v_mfma_f32_16x16x32_bf16 v[56:59], v[152:155], v[180:183], v[56:59]
	v_mfma_f32_16x16x32_bf16 v[52:55], v[172:175], v[180:183], v[52:55]
	v_mfma_f32_16x16x32_bf16 v[40:43], v[152:155], v[210:213], v[40:43]
	v_mfma_f32_16x16x32_bf16 v[36:39], v[172:175], v[210:213], v[36:39]
	v_mfma_f32_16x16x32_bf16 v[22:25], v[152:155], v[236:239], v[22:25]
	v_mfma_f32_16x16x32_bf16 v[18:21], v[172:175], v[236:239], v[18:21]
	v_mfma_f32_16x16x32_bf16 v[6:9], v[152:155], v[244:247], v[6:9]
	v_mfma_f32_16x16x32_bf16 v[2:5], v[172:175], v[244:247], v[2:5]
	s_barrier
	s_add_i32 s60, s60, 2
	s_add_u32 s58, s58, 0x10000
	s_addc_u32 s59, s59, 0
	s_cmpk_gt_u32 s60, 0xa9
	s_mov_b64 s[22:23], s[42:43]
	s_cbranch_scc0 .LBB0_1261
	s_and_b64 vcc, exec, s[46:47]
	s_cbranch_vccz .LBB0_1264
	s_barrier
